# grid barrier: the XCD leader skips the L2 writeback after the two phases whose only stores are write-through (sc1) H rows
# baseline (speedup 1.0000x reference)
.LBB0_206:
	s_andn2_saveexec_b64 s[6:7], s[10:11]
	s_cbranch_execz .LBB0_226
	s_mov_b64 s[10:11], exec
	s_cmp_eq_u32 s92, 2
	s_cbranch_scc1 .Lxb_nowb
	s_cmp_eq_u32 s92, 6
	s_cbranch_scc1 .Lxb_nowb
	buffer_wbl2 sc1
.Lxb_nowb:
	s_waitcnt lgkmcnt(0)
	s_waitcnt vmcnt(0)
	v_mbcnt_lo_u32_b32 v0, s10, 0
	v_mbcnt_hi_u32_b32 v0, s11, v0
	v_cmp_eq_u32_e32 vcc, 0, v0
	s_and_saveexec_b64 s[18:19], vcc
	s_cbranch_execz .LBB0_209
	s_bcnt1_i32_b64 s2, s[10:11]
	v_readlane_b32 s6, v254, 54
	v_mov_b32_e32 v3, s2
	v_readlane_b32 s7, v254, 55
	s_nop 4
	global_atomic_add v3, v1, v3, s[6:7] sc0
